# resid epilogue h loads batched (2 round trips), final grid barrier skipped on last layer, cache-latent conversion loop unrolled x8
# speedup vs baseline: 1.0167x; 1.0020x over previous
.LBB0_321:
	s_or_b64 exec, exec, s[18:19]
	s_ashr_i32 s17, s16, 31
	s_sub_i32 s18, s29, 64
	s_ashr_i32 s19, s18, 31
	s_lshl_b64 s[0:1], s[16:17], 21
	s_add_u32 s16, s12, s0
	s_addc_u32 s17, s13, s1
	s_and_b64 s[0:1], exec, s[4:5]
	s_cselect_b32 s1, s19, s30
	s_cselect_b32 s0, s18, s29
	s_cselect_b32 s4, s17, s9
	s_cselect_b32 s5, s16, s8
	s_lshl_b64 s[0:1], s[0:1], 20
	v_mov_b32_e32 v0, v166
	s_add_u32 s0, s5, s0
	s_addc_u32 s1, s4, s1
	v_and_b32_e32 v130, 15, v0
	v_ashrrev_i32_e32 v131, 2, v0
	s_movk_i32 s4, 0xffc0
	v_and_or_b32 v134, v131, s4, v130
	s_lshl_b32 s4, s31, 2
	s_add_u32 s0, s0, s4
	v_lshlrev_b32_e32 v132, 1, v0
	s_addc_u32 s1, s1, 0
	v_and_b32_e32 v0, 0x180, v132
	v_lshl_add_u64 v[130:131], s[0:1], 0, v[0:1]
	v_and_b32_e32 v0, 0x60, v132
	v_ashrrev_i32_e32 v135, 31, v134
	v_lshl_add_u64 v[136:137], v[130:131], 0, v[0:1]
	v_lshlrev_b64 v[130:131], 12, v[134:135]
	v_cndmask_b32_e64 v0, 0, 1, s[14:15]
	v_lshl_add_u64 v[138:139], v[136:137], 0, v[130:131]
	v_cmp_ne_u32_e64 s[4:5], 1, v0
	s_andn2_b64 vcc, exec, s[14:15]
	s_mov_b64 s[14:15], -1
	s_cbranch_vccnz .LBB0_323
	s_mov_b64 s[0:1], 0x10000
	v_lshl_add_u64 v[144:145], v[138:139], 0, s[0:1]
	s_mov_b64 s[0:1], 0x20000
	v_lshl_add_u64 v[146:147], v[138:139], 0, s[0:1]
	s_mov_b64 s[0:1], 0x30000
	v_lshl_add_u64 v[148:149], v[138:139], 0, s[0:1]
	global_load_dwordx4 v[170:173], v[138:139], off
	global_load_dwordx4 v[174:177], v[138:139], off offset:16
	global_load_dwordx4 v[178:181], v[138:139], off offset:512
	global_load_dwordx4 v[182:185], v[138:139], off offset:528
	global_load_dwordx4 v[186:189], v[144:145], off
	global_load_dwordx4 v[190:193], v[144:145], off offset:16
	global_load_dwordx4 v[194:197], v[144:145], off offset:512
	global_load_dwordx4 v[198:201], v[144:145], off offset:528
	global_load_dwordx4 v[202:205], v[146:147], off
	global_load_dwordx4 v[206:209], v[146:147], off offset:16
	global_load_dwordx4 v[210:213], v[146:147], off offset:512
	global_load_dwordx4 v[214:217], v[146:147], off offset:528
	global_load_dwordx4 v[218:221], v[148:149], off
	global_load_dwordx4 v[222:225], v[148:149], off offset:16
	global_load_dwordx4 v[226:229], v[148:149], off offset:512
	global_load_dwordx4 v[230:233], v[148:149], off offset:528
	s_mov_b64 s[0:1], 0x80000
	v_lshl_add_u64 v[150:151], v[138:139], 0, s[0:1]
	s_mov_b64 s[0:1], 0x90000
	v_lshl_add_u64 v[152:153], v[138:139], 0, s[0:1]
	s_mov_b64 s[0:1], 0xa0000
	v_lshl_add_u64 v[154:155], v[138:139], 0, s[0:1]
	s_mov_b64 s[0:1], 0xb0000
	v_lshl_add_u64 v[156:157], v[138:139], 0, s[0:1]
	s_waitcnt vmcnt(0)
	v_pk_fma_f32 v[126:127], v[126:127], 0.5, v[170:171] op_sel_hi:[1,0,1]
	v_pk_fma_f32 v[128:129], v[128:129], 0.5, v[172:173] op_sel_hi:[1,0,1]
	v_pk_fma_f32 v[122:123], v[122:123], 0.5, v[174:175] op_sel_hi:[1,0,1]
	v_pk_fma_f32 v[124:125], v[124:125], 0.5, v[176:177] op_sel_hi:[1,0,1]
	v_pk_fma_f32 v[118:119], v[118:119], 0.5, v[178:179] op_sel_hi:[1,0,1]
	v_pk_fma_f32 v[120:121], v[120:121], 0.5, v[180:181] op_sel_hi:[1,0,1]
	v_pk_fma_f32 v[114:115], v[114:115], 0.5, v[182:183] op_sel_hi:[1,0,1]
	v_pk_fma_f32 v[116:117], v[116:117], 0.5, v[184:185] op_sel_hi:[1,0,1]
	v_pk_fma_f32 v[110:111], v[110:111], 0.5, v[186:187] op_sel_hi:[1,0,1]
	v_pk_fma_f32 v[112:113], v[112:113], 0.5, v[188:189] op_sel_hi:[1,0,1]
	v_pk_fma_f32 v[106:107], v[106:107], 0.5, v[190:191] op_sel_hi:[1,0,1]
	v_pk_fma_f32 v[108:109], v[108:109], 0.5, v[192:193] op_sel_hi:[1,0,1]
	v_pk_fma_f32 v[102:103], v[102:103], 0.5, v[194:195] op_sel_hi:[1,0,1]
	v_pk_fma_f32 v[104:105], v[104:105], 0.5, v[196:197] op_sel_hi:[1,0,1]
	v_pk_fma_f32 v[98:99], v[98:99], 0.5, v[198:199] op_sel_hi:[1,0,1]
	v_pk_fma_f32 v[100:101], v[100:101], 0.5, v[200:201] op_sel_hi:[1,0,1]
	v_pk_fma_f32 v[94:95], v[94:95], 0.5, v[202:203] op_sel_hi:[1,0,1]
	v_pk_fma_f32 v[96:97], v[96:97], 0.5, v[204:205] op_sel_hi:[1,0,1]
	v_pk_fma_f32 v[90:91], v[90:91], 0.5, v[206:207] op_sel_hi:[1,0,1]
	v_pk_fma_f32 v[92:93], v[92:93], 0.5, v[208:209] op_sel_hi:[1,0,1]
	v_pk_fma_f32 v[86:87], v[86:87], 0.5, v[210:211] op_sel_hi:[1,0,1]
	v_pk_fma_f32 v[88:89], v[88:89], 0.5, v[212:213] op_sel_hi:[1,0,1]
	v_pk_fma_f32 v[82:83], v[82:83], 0.5, v[214:215] op_sel_hi:[1,0,1]
	v_pk_fma_f32 v[84:85], v[84:85], 0.5, v[216:217] op_sel_hi:[1,0,1]
	v_pk_fma_f32 v[78:79], v[78:79], 0.5, v[218:219] op_sel_hi:[1,0,1]
	v_pk_fma_f32 v[80:81], v[80:81], 0.5, v[220:221] op_sel_hi:[1,0,1]
	v_pk_fma_f32 v[74:75], v[74:75], 0.5, v[222:223] op_sel_hi:[1,0,1]
	v_pk_fma_f32 v[76:77], v[76:77], 0.5, v[224:225] op_sel_hi:[1,0,1]
	v_pk_fma_f32 v[70:71], v[70:71], 0.5, v[226:227] op_sel_hi:[1,0,1]
	v_pk_fma_f32 v[72:73], v[72:73], 0.5, v[228:229] op_sel_hi:[1,0,1]
	v_pk_fma_f32 v[66:67], v[66:67], 0.5, v[230:231] op_sel_hi:[1,0,1]
	v_pk_fma_f32 v[68:69], v[68:69], 0.5, v[232:233] op_sel_hi:[1,0,1]
	global_load_dwordx4 v[170:173], v[150:151], off
	global_load_dwordx4 v[174:177], v[150:151], off offset:16
	global_load_dwordx4 v[178:181], v[150:151], off offset:512
	global_load_dwordx4 v[182:185], v[150:151], off offset:528
	global_load_dwordx4 v[186:189], v[152:153], off
	global_load_dwordx4 v[190:193], v[152:153], off offset:16
	global_load_dwordx4 v[194:197], v[152:153], off offset:512
	global_load_dwordx4 v[198:201], v[152:153], off offset:528
	global_load_dwordx4 v[202:205], v[154:155], off
	global_load_dwordx4 v[206:209], v[154:155], off offset:16
	global_load_dwordx4 v[210:213], v[154:155], off offset:512
	global_load_dwordx4 v[214:217], v[154:155], off offset:528
	global_load_dwordx4 v[218:221], v[156:157], off
	global_load_dwordx4 v[222:225], v[156:157], off offset:16
	global_load_dwordx4 v[226:229], v[156:157], off offset:512
	global_load_dwordx4 v[230:233], v[156:157], off offset:528
	global_store_dwordx4 v[138:139], v[126:129], off
	global_store_dwordx4 v[138:139], v[122:125], off offset:16
	global_store_dwordx4 v[138:139], v[118:121], off offset:512
	global_store_dwordx4 v[138:139], v[114:117], off offset:528
	global_store_dwordx4 v[144:145], v[110:113], off
	global_store_dwordx4 v[144:145], v[106:109], off offset:16
	global_store_dwordx4 v[144:145], v[102:105], off offset:512
	global_store_dwordx4 v[144:145], v[98:101], off offset:528
	global_store_dwordx4 v[146:147], v[94:97], off
	global_store_dwordx4 v[146:147], v[90:93], off offset:16
	global_store_dwordx4 v[146:147], v[86:89], off offset:512
	global_store_dwordx4 v[146:147], v[82:85], off offset:528
	global_store_dwordx4 v[148:149], v[78:81], off
	global_store_dwordx4 v[148:149], v[74:77], off offset:16
	global_store_dwordx4 v[148:149], v[70:73], off offset:512
	global_store_dwordx4 v[148:149], v[66:69], off offset:528
	s_waitcnt vmcnt(16)
	v_pk_fma_f32 v[62:63], v[62:63], 0.5, v[170:171] op_sel_hi:[1,0,1]
	v_pk_fma_f32 v[64:65], v[64:65], 0.5, v[172:173] op_sel_hi:[1,0,1]
	v_pk_fma_f32 v[58:59], v[58:59], 0.5, v[174:175] op_sel_hi:[1,0,1]
	v_pk_fma_f32 v[60:61], v[60:61], 0.5, v[176:177] op_sel_hi:[1,0,1]
	v_pk_fma_f32 v[54:55], v[54:55], 0.5, v[178:179] op_sel_hi:[1,0,1]
	v_pk_fma_f32 v[56:57], v[56:57], 0.5, v[180:181] op_sel_hi:[1,0,1]
	v_pk_fma_f32 v[50:51], v[50:51], 0.5, v[182:183] op_sel_hi:[1,0,1]
	v_pk_fma_f32 v[52:53], v[52:53], 0.5, v[184:185] op_sel_hi:[1,0,1]
	v_pk_fma_f32 v[46:47], v[46:47], 0.5, v[186:187] op_sel_hi:[1,0,1]
	v_pk_fma_f32 v[48:49], v[48:49], 0.5, v[188:189] op_sel_hi:[1,0,1]
	v_pk_fma_f32 v[42:43], v[42:43], 0.5, v[190:191] op_sel_hi:[1,0,1]
	v_pk_fma_f32 v[44:45], v[44:45], 0.5, v[192:193] op_sel_hi:[1,0,1]
	v_pk_fma_f32 v[38:39], v[38:39], 0.5, v[194:195] op_sel_hi:[1,0,1]
	v_pk_fma_f32 v[40:41], v[40:41], 0.5, v[196:197] op_sel_hi:[1,0,1]
	v_pk_fma_f32 v[34:35], v[34:35], 0.5, v[198:199] op_sel_hi:[1,0,1]
	v_pk_fma_f32 v[36:37], v[36:37], 0.5, v[200:201] op_sel_hi:[1,0,1]
	v_pk_fma_f32 v[30:31], v[30:31], 0.5, v[202:203] op_sel_hi:[1,0,1]
	v_pk_fma_f32 v[32:33], v[32:33], 0.5, v[204:205] op_sel_hi:[1,0,1]
	v_pk_fma_f32 v[26:27], v[26:27], 0.5, v[206:207] op_sel_hi:[1,0,1]
	v_pk_fma_f32 v[28:29], v[28:29], 0.5, v[208:209] op_sel_hi:[1,0,1]
	v_pk_fma_f32 v[22:23], v[22:23], 0.5, v[210:211] op_sel_hi:[1,0,1]
	v_pk_fma_f32 v[24:25], v[24:25], 0.5, v[212:213] op_sel_hi:[1,0,1]
	v_pk_fma_f32 v[18:19], v[18:19], 0.5, v[214:215] op_sel_hi:[1,0,1]
	v_pk_fma_f32 v[20:21], v[20:21], 0.5, v[216:217] op_sel_hi:[1,0,1]
	v_pk_fma_f32 v[14:15], v[14:15], 0.5, v[218:219] op_sel_hi:[1,0,1]
	v_pk_fma_f32 v[16:17], v[16:17], 0.5, v[220:221] op_sel_hi:[1,0,1]
	v_pk_fma_f32 v[10:11], v[10:11], 0.5, v[222:223] op_sel_hi:[1,0,1]
	v_pk_fma_f32 v[12:13], v[12:13], 0.5, v[224:225] op_sel_hi:[1,0,1]
	v_pk_fma_f32 v[6:7], v[6:7], 0.5, v[226:227] op_sel_hi:[1,0,1]
	v_pk_fma_f32 v[8:9], v[8:9], 0.5, v[228:229] op_sel_hi:[1,0,1]
	v_pk_fma_f32 v[2:3], v[2:3], 0.5, v[230:231] op_sel_hi:[1,0,1]
	v_pk_fma_f32 v[4:5], v[4:5], 0.5, v[232:233] op_sel_hi:[1,0,1]
	global_store_dwordx4 v[150:151], v[62:65], off
	global_store_dwordx4 v[150:151], v[58:61], off offset:16
	global_store_dwordx4 v[150:151], v[54:57], off offset:512
	global_store_dwordx4 v[150:151], v[50:53], off offset:528
	global_store_dwordx4 v[152:153], v[46:49], off
	global_store_dwordx4 v[152:153], v[42:45], off offset:16
	global_store_dwordx4 v[152:153], v[38:41], off offset:512
	global_store_dwordx4 v[152:153], v[34:37], off offset:528
	global_store_dwordx4 v[154:155], v[30:33], off
	global_store_dwordx4 v[154:155], v[26:29], off offset:16
	global_store_dwordx4 v[154:155], v[22:25], off offset:512
	global_store_dwordx4 v[154:155], v[18:21], off offset:528
	global_store_dwordx4 v[156:157], v[14:17], off
	global_store_dwordx4 v[156:157], v[10:13], off offset:16
	global_store_dwordx4 v[156:157], v[6:9], off offset:512
	global_store_dwordx4 v[156:157], v[2:5], off offset:528
	v_readlane_b32 s0, v243, 0
	s_add_i32 s24, s24, s0
	s_cmpk_lt_i32 s24, 0x158
	v_readlane_b32 s1, v243, 1
	s_cbranch_scc0 .LBB0_385
	s_branch .LBB0_310

.LBB0_544:
	s_or_b64 exec, exec, s[28:29]
	v_readlane_b32 s0, v243, 4
	s_mov_b32 s6, s83
	v_readlane_b32 s1, v243, 5
	s_load_dword s4, s[0:1], 0x0
	s_load_dword s5, s[0:1], 0x10
	s_ashr_i32 s7, s6, 31
	s_lshl_b64 s[0:1], s[6:7], 9
	v_ashrrev_i32_e32 v3, 31, v2
	v_lshl_add_u64 v[6:7], s[0:1], 0, v[2:3]
	s_waitcnt lgkmcnt(0)
	s_lshr_b32 s0, s5, 16
	s_cmp_lg_u32 s0, 0
	s_cselect_b64 s[0:1], -1, 0
	s_cmp_lg_u64 s[0:1], 0
	s_addc_u32 s44, s4, 0
	s_mov_b64 s[0:1], 0x800000
	s_lshl_b64 s[4:5], s[44:45], 9
	v_cmp_gt_i64_e32 vcc, s[0:1], v[6:7]
	v_lshlrev_b64 v[4:5], 5, v[2:3]
	s_and_saveexec_b64 s[8:9], vcc
	s_cbranch_execz .LBB0_547
	v_readlane_b32 s0, v243, 29
	v_readlane_b32 s1, v243, 30
	s_load_dwordx2 s[12:13], s[26:27], 0x10
	s_load_dwordx2 s[14:15], s[26:27], 0xf0
	s_lshl_b64 s[0:1], s[0:1], 28
	s_lshl_b64 s[16:17], s[6:7], 14
	s_add_u32 s0, s0, s16
	s_addc_u32 s1, s1, s17
	s_waitcnt lgkmcnt(0)
	s_add_u32 s0, s12, s0
	s_addc_u32 s1, s13, s1
	v_lshl_add_u64 v[8:9], s[0:1], 0, v[4:5]
	s_lshl_b64 s[12:13], s[44:45], 14
	s_lshl_b64 s[0:1], s[6:7], 13
	s_add_u32 s0, s14, s0
	s_addc_u32 s1, s15, s1
	v_lshl_add_u64 v[10:11], v[2:3], 4, s[0:1]
	v_lshl_add_u64 v[8:9], v[8:9], 0, 16
	v_lshl_add_u64 v[10:11], v[10:11], 0, 8
	s_lshl_b64 s[14:15], s[44:45], 13
	s_mov_b64 s[16:17], 0
	v_mov_b64_e32 v[12:13], v[6:7]
	v_readlane_b32 s20, v6, 63
	v_readlane_b32 s21, v7, 63
	s_lshl_b64 s[18:19], s[4:5], 3
	s_lshl_b64 s[48:49], s[12:13], 3
	s_lshl_b64 s[52:53], s[14:15], 3
	s_sub_u32 s0, s18, s4
	s_subb_u32 s1, s19, s5
	s_add_u32 s20, s20, s0
	s_addc_u32 s21, s21, s1
.Lcb8_head:
	s_cmp_lg_u32 s21, 0
	s_cbranch_scc1 .Lcb8_done
	s_cmp_ge_u32 s20, 0x800000
	s_cbranch_scc1 .Lcb8_done
	global_load_dwordx4 v[40:43], v[8:9], off offset:-16 nt
	global_load_dwordx4 v[44:47], v[8:9], off nt
	v_lshl_add_u64 v[22:23], v[8:9], 0, s[12:13]
	global_load_dwordx4 v[48:51], v[22:23], off offset:-16 nt
	global_load_dwordx4 v[52:55], v[22:23], off nt
	v_lshl_add_u64 v[24:25], v[22:23], 0, s[12:13]
	global_load_dwordx4 v[56:59], v[24:25], off offset:-16 nt
	global_load_dwordx4 v[60:63], v[24:25], off nt
	v_lshl_add_u64 v[26:27], v[24:25], 0, s[12:13]
	global_load_dwordx4 v[64:67], v[26:27], off offset:-16 nt
	global_load_dwordx4 v[68:71], v[26:27], off nt
	v_lshl_add_u64 v[28:29], v[26:27], 0, s[12:13]
	global_load_dwordx4 v[72:75], v[28:29], off offset:-16 nt
	global_load_dwordx4 v[76:79], v[28:29], off nt
	v_lshl_add_u64 v[30:31], v[28:29], 0, s[12:13]
	global_load_dwordx4 v[80:83], v[30:31], off offset:-16 nt
	global_load_dwordx4 v[84:87], v[30:31], off nt
	v_lshl_add_u64 v[32:33], v[30:31], 0, s[12:13]
	global_load_dwordx4 v[88:91], v[32:33], off offset:-16 nt
	global_load_dwordx4 v[92:95], v[32:33], off nt
	v_lshl_add_u64 v[34:35], v[32:33], 0, s[12:13]
	global_load_dwordx4 v[96:99], v[34:35], off offset:-16 nt
	global_load_dwordx4 v[100:103], v[34:35], off nt
	v_lshl_add_u64 v[104:105], v[10:11], 0, s[14:15]
	v_lshl_add_u64 v[106:107], v[104:105], 0, s[14:15]
	v_lshl_add_u64 v[108:109], v[106:107], 0, s[14:15]
	v_lshl_add_u64 v[110:111], v[108:109], 0, s[14:15]
	v_lshl_add_u64 v[112:113], v[110:111], 0, s[14:15]
	v_lshl_add_u64 v[114:115], v[112:113], 0, s[14:15]
	v_lshl_add_u64 v[116:117], v[114:115], 0, s[14:15]
	s_waitcnt vmcnt(14)
	v_cvt_pk_bf16_f32 v40, v40, v41
	v_cvt_pk_bf16_f32 v41, v42, v43
	v_cvt_pk_bf16_f32 v42, v44, v45
	v_cvt_pk_bf16_f32 v43, v46, v47
	global_store_dwordx4 v[10:11], v[40:43], off offset:-8
	s_waitcnt vmcnt(13)
	v_cvt_pk_bf16_f32 v48, v48, v49
	v_cvt_pk_bf16_f32 v49, v50, v51
	v_cvt_pk_bf16_f32 v50, v52, v53
	v_cvt_pk_bf16_f32 v51, v54, v55
	global_store_dwordx4 v[104:105], v[48:51], off offset:-8
	s_waitcnt vmcnt(12)
	v_cvt_pk_bf16_f32 v56, v56, v57
	v_cvt_pk_bf16_f32 v57, v58, v59
	v_cvt_pk_bf16_f32 v58, v60, v61
	v_cvt_pk_bf16_f32 v59, v62, v63
	global_store_dwordx4 v[106:107], v[56:59], off offset:-8
	s_waitcnt vmcnt(11)
	v_cvt_pk_bf16_f32 v64, v64, v65
	v_cvt_pk_bf16_f32 v65, v66, v67
	v_cvt_pk_bf16_f32 v66, v68, v69
	v_cvt_pk_bf16_f32 v67, v70, v71
	global_store_dwordx4 v[108:109], v[64:67], off offset:-8
	s_waitcnt vmcnt(10)
	v_cvt_pk_bf16_f32 v72, v72, v73
	v_cvt_pk_bf16_f32 v73, v74, v75
	v_cvt_pk_bf16_f32 v74, v76, v77
	v_cvt_pk_bf16_f32 v75, v78, v79
	global_store_dwordx4 v[110:111], v[72:75], off offset:-8
	s_waitcnt vmcnt(9)
	v_cvt_pk_bf16_f32 v80, v80, v81
	v_cvt_pk_bf16_f32 v81, v82, v83
	v_cvt_pk_bf16_f32 v82, v84, v85
	v_cvt_pk_bf16_f32 v83, v86, v87
	global_store_dwordx4 v[112:113], v[80:83], off offset:-8
	s_waitcnt vmcnt(8)
	v_cvt_pk_bf16_f32 v88, v88, v89
	v_cvt_pk_bf16_f32 v89, v90, v91
	v_cvt_pk_bf16_f32 v90, v92, v93
	v_cvt_pk_bf16_f32 v91, v94, v95
	global_store_dwordx4 v[114:115], v[88:91], off offset:-8
	s_waitcnt vmcnt(7)
	v_cvt_pk_bf16_f32 v96, v96, v97
	v_cvt_pk_bf16_f32 v97, v98, v99
	v_cvt_pk_bf16_f32 v98, v100, v101
	v_cvt_pk_bf16_f32 v99, v102, v103
	global_store_dwordx4 v[116:117], v[96:99], off offset:-8
	v_lshl_add_u64 v[8:9], v[8:9], 0, s[48:49]
	v_lshl_add_u64 v[10:11], v[10:11], 0, s[52:53]
	v_lshl_add_u64 v[12:13], v[12:13], 0, s[18:19]
	s_add_u32 s20, s20, s18
	s_addc_u32 s21, s21, s19
	s_branch .Lcb8_head
.Lcb8_done:
	s_mov_b64 s[0:1], 0x800000
	v_cmp_gt_i64_e32 vcc, s[0:1], v[12:13]
	s_and_b64 exec, exec, vcc
	s_cbranch_execz .LBB0_547

.LBB0_1120:
	s_or_b64 exec, exec, s[20:21]
	s_ashr_i32 s19, s18, 31
	s_sub_i32 s20, s16, 64
	s_ashr_i32 s21, s20, 31
	s_lshl_b64 s[0:1], s[18:19], 21
	s_add_u32 s18, s12, s0
	s_addc_u32 s19, s13, s1
	s_and_b64 s[0:1], exec, s[4:5]
	s_cselect_b32 s1, s21, s17
	s_cselect_b32 s0, s20, s16
	s_cselect_b32 s4, s19, s9
	s_cselect_b32 s5, s18, s8
	s_lshl_b64 s[0:1], s[0:1], 20
	v_mov_b32_e32 v0, v166
	s_add_u32 s0, s5, s0
	s_addc_u32 s1, s4, s1
	v_and_b32_e32 v130, 15, v0
	v_ashrrev_i32_e32 v131, 2, v0
	s_movk_i32 s4, 0xffc0
	v_and_or_b32 v134, v131, s4, v130
	s_lshl_b32 s4, s35, 2
	s_add_u32 s0, s0, s4
	v_lshlrev_b32_e32 v132, 1, v0
	s_addc_u32 s1, s1, 0
	v_and_b32_e32 v0, 0x180, v132
	v_lshl_add_u64 v[130:131], s[0:1], 0, v[0:1]
	v_and_b32_e32 v0, 0x60, v132
	v_ashrrev_i32_e32 v135, 31, v134
	v_lshl_add_u64 v[136:137], v[130:131], 0, v[0:1]
	v_lshlrev_b64 v[130:131], 12, v[134:135]
	v_cndmask_b32_e64 v0, 0, 1, s[14:15]
	v_lshl_add_u64 v[138:139], v[136:137], 0, v[130:131]
	v_cmp_ne_u32_e64 s[4:5], 1, v0
	s_andn2_b64 vcc, exec, s[14:15]
	s_mov_b64 s[14:15], -1
	s_cbranch_vccnz .LBB0_1122
	s_mov_b64 s[0:1], 0x10000
	v_lshl_add_u64 v[144:145], v[138:139], 0, s[0:1]
	s_mov_b64 s[0:1], 0x20000
	v_lshl_add_u64 v[146:147], v[138:139], 0, s[0:1]
	s_mov_b64 s[0:1], 0x30000
	v_lshl_add_u64 v[148:149], v[138:139], 0, s[0:1]
	global_load_dwordx4 v[170:173], v[138:139], off
	global_load_dwordx4 v[174:177], v[138:139], off offset:16
	global_load_dwordx4 v[178:181], v[138:139], off offset:512
	global_load_dwordx4 v[182:185], v[138:139], off offset:528
	global_load_dwordx4 v[186:189], v[144:145], off
	global_load_dwordx4 v[190:193], v[144:145], off offset:16
	global_load_dwordx4 v[194:197], v[144:145], off offset:512
	global_load_dwordx4 v[198:201], v[144:145], off offset:528
	global_load_dwordx4 v[202:205], v[146:147], off
	global_load_dwordx4 v[206:209], v[146:147], off offset:16
	global_load_dwordx4 v[210:213], v[146:147], off offset:512
	global_load_dwordx4 v[214:217], v[146:147], off offset:528
	global_load_dwordx4 v[218:221], v[148:149], off
	global_load_dwordx4 v[222:225], v[148:149], off offset:16
	global_load_dwordx4 v[226:229], v[148:149], off offset:512
	global_load_dwordx4 v[230:233], v[148:149], off offset:528
	s_mov_b64 s[0:1], 0x80000
	v_lshl_add_u64 v[150:151], v[138:139], 0, s[0:1]
	s_mov_b64 s[0:1], 0x90000
	v_lshl_add_u64 v[152:153], v[138:139], 0, s[0:1]
	s_mov_b64 s[0:1], 0xa0000
	v_lshl_add_u64 v[154:155], v[138:139], 0, s[0:1]
	s_mov_b64 s[0:1], 0xb0000
	v_lshl_add_u64 v[156:157], v[138:139], 0, s[0:1]
	s_waitcnt vmcnt(0)
	v_pk_add_f32 v[126:127], v[126:127], v[170:171]
	v_pk_add_f32 v[128:129], v[128:129], v[172:173]
	v_pk_add_f32 v[122:123], v[122:123], v[174:175]
	v_pk_add_f32 v[124:125], v[124:125], v[176:177]
	v_pk_add_f32 v[118:119], v[118:119], v[178:179]
	v_pk_add_f32 v[120:121], v[120:121], v[180:181]
	v_pk_add_f32 v[114:115], v[114:115], v[182:183]
	v_pk_add_f32 v[116:117], v[116:117], v[184:185]
	v_pk_add_f32 v[110:111], v[110:111], v[186:187]
	v_pk_add_f32 v[112:113], v[112:113], v[188:189]
	v_pk_add_f32 v[106:107], v[106:107], v[190:191]
	v_pk_add_f32 v[108:109], v[108:109], v[192:193]
	v_pk_add_f32 v[102:103], v[102:103], v[194:195]
	v_pk_add_f32 v[104:105], v[104:105], v[196:197]
	v_pk_add_f32 v[98:99], v[98:99], v[198:199]
	v_pk_add_f32 v[100:101], v[100:101], v[200:201]
	v_pk_add_f32 v[94:95], v[94:95], v[202:203]
	v_pk_add_f32 v[96:97], v[96:97], v[204:205]
	v_pk_add_f32 v[90:91], v[90:91], v[206:207]
	v_pk_add_f32 v[92:93], v[92:93], v[208:209]
	v_pk_add_f32 v[86:87], v[86:87], v[210:211]
	v_pk_add_f32 v[88:89], v[88:89], v[212:213]
	v_pk_add_f32 v[82:83], v[82:83], v[214:215]
	v_pk_add_f32 v[84:85], v[84:85], v[216:217]
	v_pk_add_f32 v[78:79], v[78:79], v[218:219]
	v_pk_add_f32 v[80:81], v[80:81], v[220:221]
	v_pk_add_f32 v[74:75], v[74:75], v[222:223]
	v_pk_add_f32 v[76:77], v[76:77], v[224:225]
	v_pk_add_f32 v[70:71], v[70:71], v[226:227]
	v_pk_add_f32 v[72:73], v[72:73], v[228:229]
	v_pk_add_f32 v[66:67], v[66:67], v[230:231]
	v_pk_add_f32 v[68:69], v[68:69], v[232:233]
	global_load_dwordx4 v[170:173], v[150:151], off
	global_load_dwordx4 v[174:177], v[150:151], off offset:16
	global_load_dwordx4 v[178:181], v[150:151], off offset:512
	global_load_dwordx4 v[182:185], v[150:151], off offset:528
	global_load_dwordx4 v[186:189], v[152:153], off
	global_load_dwordx4 v[190:193], v[152:153], off offset:16
	global_load_dwordx4 v[194:197], v[152:153], off offset:512
	global_load_dwordx4 v[198:201], v[152:153], off offset:528
	global_load_dwordx4 v[202:205], v[154:155], off
	global_load_dwordx4 v[206:209], v[154:155], off offset:16
	global_load_dwordx4 v[210:213], v[154:155], off offset:512
	global_load_dwordx4 v[214:217], v[154:155], off offset:528
	global_load_dwordx4 v[218:221], v[156:157], off
	global_load_dwordx4 v[222:225], v[156:157], off offset:16
	global_load_dwordx4 v[226:229], v[156:157], off offset:512
	global_load_dwordx4 v[230:233], v[156:157], off offset:528
	global_store_dwordx4 v[138:139], v[126:129], off
	global_store_dwordx4 v[138:139], v[122:125], off offset:16
	global_store_dwordx4 v[138:139], v[118:121], off offset:512
	global_store_dwordx4 v[138:139], v[114:117], off offset:528
	global_store_dwordx4 v[144:145], v[110:113], off
	global_store_dwordx4 v[144:145], v[106:109], off offset:16
	global_store_dwordx4 v[144:145], v[102:105], off offset:512
	global_store_dwordx4 v[144:145], v[98:101], off offset:528
	global_store_dwordx4 v[146:147], v[94:97], off
	global_store_dwordx4 v[146:147], v[90:93], off offset:16
	global_store_dwordx4 v[146:147], v[86:89], off offset:512
	global_store_dwordx4 v[146:147], v[82:85], off offset:528
	global_store_dwordx4 v[148:149], v[78:81], off
	global_store_dwordx4 v[148:149], v[74:77], off offset:16
	global_store_dwordx4 v[148:149], v[70:73], off offset:512
	global_store_dwordx4 v[148:149], v[66:69], off offset:528
	s_waitcnt vmcnt(16)
	v_pk_add_f32 v[62:63], v[62:63], v[170:171]
	v_pk_add_f32 v[64:65], v[64:65], v[172:173]
	v_pk_add_f32 v[58:59], v[58:59], v[174:175]
	v_pk_add_f32 v[60:61], v[60:61], v[176:177]
	v_pk_add_f32 v[54:55], v[54:55], v[178:179]
	v_pk_add_f32 v[56:57], v[56:57], v[180:181]
	v_pk_add_f32 v[50:51], v[50:51], v[182:183]
	v_pk_add_f32 v[52:53], v[52:53], v[184:185]
	v_pk_add_f32 v[46:47], v[46:47], v[186:187]
	v_pk_add_f32 v[48:49], v[48:49], v[188:189]
	v_pk_add_f32 v[42:43], v[42:43], v[190:191]
	v_pk_add_f32 v[44:45], v[44:45], v[192:193]
	v_pk_add_f32 v[38:39], v[38:39], v[194:195]
	v_pk_add_f32 v[40:41], v[40:41], v[196:197]
	v_pk_add_f32 v[34:35], v[34:35], v[198:199]
	v_pk_add_f32 v[36:37], v[36:37], v[200:201]
	v_pk_add_f32 v[30:31], v[30:31], v[202:203]
	v_pk_add_f32 v[32:33], v[32:33], v[204:205]
	v_pk_add_f32 v[26:27], v[26:27], v[206:207]
	v_pk_add_f32 v[28:29], v[28:29], v[208:209]
	v_pk_add_f32 v[22:23], v[22:23], v[210:211]
	v_pk_add_f32 v[24:25], v[24:25], v[212:213]
	v_pk_add_f32 v[18:19], v[18:19], v[214:215]
	v_pk_add_f32 v[20:21], v[20:21], v[216:217]
	v_pk_add_f32 v[14:15], v[14:15], v[218:219]
	v_pk_add_f32 v[16:17], v[16:17], v[220:221]
	v_pk_add_f32 v[10:11], v[10:11], v[222:223]
	v_pk_add_f32 v[12:13], v[12:13], v[224:225]
	v_pk_add_f32 v[6:7], v[6:7], v[226:227]
	v_pk_add_f32 v[8:9], v[8:9], v[228:229]
	v_pk_add_f32 v[2:3], v[2:3], v[230:231]
	v_pk_add_f32 v[4:5], v[4:5], v[232:233]
	global_store_dwordx4 v[150:151], v[62:65], off
	global_store_dwordx4 v[150:151], v[58:61], off offset:16
	global_store_dwordx4 v[150:151], v[54:57], off offset:512
	global_store_dwordx4 v[150:151], v[50:53], off offset:528
	global_store_dwordx4 v[152:153], v[46:49], off
	global_store_dwordx4 v[152:153], v[42:45], off offset:16
	global_store_dwordx4 v[152:153], v[38:41], off offset:512
	global_store_dwordx4 v[152:153], v[34:37], off offset:528
	global_store_dwordx4 v[154:155], v[30:33], off
	global_store_dwordx4 v[154:155], v[26:29], off offset:16
	global_store_dwordx4 v[154:155], v[22:25], off offset:512
	global_store_dwordx4 v[154:155], v[18:21], off offset:528
	global_store_dwordx4 v[156:157], v[14:17], off
	global_store_dwordx4 v[156:157], v[10:13], off offset:16
	global_store_dwordx4 v[156:157], v[6:9], off offset:512
	global_store_dwordx4 v[156:157], v[2:5], off offset:528
	v_readlane_b32 s0, v243, 0
	s_add_i32 s28, s28, s0
	s_cmpk_lt_i32 s28, 0x120
	v_readlane_b32 s1, v243, 1
	s_cbranch_scc0 .LBB0_1184
	s_branch .LBB0_1109

.LBB0_1518:
	s_waitcnt vmcnt(0)
	v_readlane_b32 s0, v243, 24
	v_readlane_b32 s1, v243, 25
	s_nop 1
	s_and_b64 vcc, exec, s[0:1]
	s_cbranch_vccnz .LBB0_1561
	s_barrier
	s_mov_b64 s[52:53], exec
	v_readlane_b32 s0, v243, 6
	v_readlane_b32 s1, v243, 7
	s_and_b64 s[0:1], s[52:53], s[0:1]
	s_mov_b64 exec, s[0:1]
	s_cbranch_execnz .LBB0_1519
	s_getpc_b64 s[98:99]
